# speedup vs baseline: 1.0053x; 1.0041x over previous
;   const int tid = tidx, lane = tid & 63, w = tid >> 6;
;   const int wm = w >> 1, wn = w & 1;
;   const int l15 = lane & 15, quad = lane >> 4;
;   constexpr int NB = (TN * 32 * 8) / NT;
;   constexpr int BUFE = (256 + (TN > 4 ? 192 : 128)) * GSTR;
;   u32x4 ra0[4], ra1[4];
;   u32x4 rb0[NB], rb1[NB];
;   const int cr = tid >> 3, ck = tid & 7;
;   const unsigned aoffb = (unsigned)(cr * lda + ck * 8) * 2u;
;   const unsigned boffb = (unsigned)(cr * ldb + ck * 8) * 2u;
.LBB0_578:
	s_andn2_b64 vcc, exec, s[10:11]
	s_cbranch_vccnz .LBB0_588
	v_readlane_b32 s10, v252, 45
	v_readlane_b32 s11, v252, 46
	s_andn2_b64 vcc, exec, s[10:11]
	s_cbranch_vccnz .LBB0_588
	s_waitcnt vmcnt(14)
	v_ashrrev_i32_e32 v10, 1, v150
	s_waitcnt lgkmcnt(0)
	v_and_b32_e32 v8, 15, v150
	v_and_b32_e32 v10, 0xffffffc0, v10
	v_lshlrev_b32_e32 v0, 4, v150
	s_movk_i32 s5, 0xa0
	v_or_b32_e32 v11, v10, v8
	v_ashrrev_i32_e32 v2, 3, v150
	v_and_b32_e32 v3, 0x70, v0
	v_mul_lo_u32 v20, v11, s5
	s_add_i32 s0, 0, 0xf000
	v_lshl_or_b32 v0, v2, 11, v3
	v_add_u32_e32 v9, 0, v3
	v_mul_lo_u32 v2, v2, s5
	v_add_u32_e32 v11, s0, v20
	v_readlane_b32 s0, v254, 12
	v_and_b32_e32 v18, 48, v150
	s_waitcnt vmcnt(13)
	v_and_b32_e32 v12, 0x4f, v150
	v_add_u32_e32 v22, v9, v2
	v_mov_b32_e32 v9, s0
	v_lshrrev_b32_e32 v17, 2, v150
	v_add_u32_e32 v19, 0, v18
	v_add_u32_e32 v14, s0, v18
	v_lshrrev_b32_e32 v23, 3, v150
	v_mul_u32_u24_e32 v23, 0xa0, v23
	v_add_u32_e32 v23, 0xa000, v23
	v_add_u32_e32 v23, v23, v3
	s_waitcnt vmcnt(11)
	v_mad_u32_u24 v28, v12, s5, v9
	v_and_or_b32 v10, v17, 12, v10
	v_and_b32_e32 v17, 64, v150
	s_movk_i32 s0, 0x110
	v_mul_u32_u24_e32 v21, 0xa0, v12
	v_add_u32_e32 v13, 0xf000, v19
	s_waitcnt vmcnt(8)
	v_add_u32_e32 v15, 0, v20
	v_mad_u32_u24 v16, v12, s5, 0
	v_add_u32_e32 v2, 0x1400, v11
	v_add_u32_e32 v3, 0x1e00, v11
	v_add_u32_e32 v9, 0xa00, v28
	v_add_u32_e32 v11, 0x1400, v28
	v_add_u32_e32 v12, 0x1e00, v28
	v_lshl_add_u32 v17, v17, 1, 0
	v_lshlrev_b32_e32 v8, 1, v8
	v_mul_lo_u32 v10, v10, s0
	v_add_u32_e32 v24, 0x2800, v22
	v_add_u32_e32 v25, 0x2800, v23
	v_add_u32_e32 v26, 0x5000, v22
	v_add_u32_e32 v27, 0x7800, v22
	v_add3_u32 v29, v17, v8, v10
	v_cmp_gt_i32_e64 s[10:11], s36, v150
	s_mov_b32 s0, 0
	v_add_u32_e32 v30, v15, v18
	v_add_u32_e32 v31, v16, v18
	v_add_u32_e32 v32, v13, v20
	v_add_u32_e32 v33, v14, v21
	v_add_u32_e32 v34, v2, v18
	v_add_u32_e32 v35, v3, v18
	v_add_u32_e32 v36, v9, v18
	v_add_u32_e32 v37, v11, v18
	v_add_u32_e32 v38, v12, v18
	v_lshrrev_b32_e32 v170, 1, v150
	v_and_b32_e32 v171, 1, v150
	v_lshlrev_b32_e32 v170, 11, v170
	v_lshl_or_b32 v170, v171, 7, v170
	v_and_b32_e32 v171, 3, v150
	v_lshlrev_b32_e32 v171, 7, v171
	v_lshrrev_b32_e32 v172, 2, v150
	v_lshl_or_b32 v171, v172, 11, v171
	v_lshrrev_b32_e32 v172, 3, v150
	v_and_b32_e32 v173, 12, v172
	v_lshlrev_b32_e32 v173, 1, v173
	v_and_or_b32 v173, v172, 35, v173
	v_and_b32_e32 v172, 16, v172
	v_lshrrev_b32_e32 v172, 2, v172
	v_or_b32_e32 v172, v173, v172
	v_and_b32_e32 v173, 7, v150
	v_lshlrev_b32_e32 v173, 4, v173
	v_lshl_or_b32 v172, v172, 11, v173
	v_mov_b32_e32 v173, 0
	v_readlane_b32 s18, v251, 0
	s_branch .LBB0_582

;     ...
;   G_LOAD(ra0, rb0, 0);
;   G_LOAD(ra1, rb1, 64);
;   __syncthreads();
;   G_STORE(ra0, rb0, 0);
;   __syncthreads();
;   G_READ(fa0, fb0, 0, 0);
; #pragma unroll
;   for (int k0 = 0; k0 < K; k0 += 128) {
;     G_READ(fa1, fb1, 0, 32);
;     if (k0 + 128 < K) G_LOAD(ra0, rb0, k0 + 128);
;     __builtin_amdgcn_sched_barrier(0);
;     G_MFMA_ST(fa0, fb0, ra1, rb1, 1);
;     __syncthreads();
;     G_READ(fa0, fb0, 1, 0);
;     __builtin_amdgcn_sched_barrier(0);
;     G_MFMA(fa1, fb1);
; __device__ __forceinline__ void phase_inproj(const Params& p, const int tidx) {
;     ...
;   for (int tile = blockIdx.x, rnd = 0; tile < 128 * NTN; tile += gridDim.x, rnd++) {
;     int mt = tile / NTN, nt = tile % NTN;
;     if (swz) {
;       int j = rnd * 32 + li;
;       int g = j / (4 * NTN), rem = j % (4 * NTN);
;       nt = rem >> 2;
;       mt = xcd * 16 + g * 4 + (rem & 3);
;     }
;     f32x4 acc[4][4];
;     zero_acc<4>(acc);
;     gemm_main<4, 1024>(acc, H + (size_t)mt * 256 * 1024, 1024, W + (size_t)nt * 128 * 1024, 1024, sA, sB, tidx);
.LBB0_585:
	s_ashr_i32 s15, s14, 31
	s_lshl_b64 s[16:17], s[14:15], 19
	s_add_u32 s16, s50, s16
	s_addc_u32 s17, s51, s17
	v_lshl_add_u64 v[2:3], s[16:17], 0, v[0:1]
	s_mov_b32 s5, 0x20000
	s_ashr_i32 s13, s12, 31
	v_add_co_u32_e32 v8, vcc, s5, v2
	s_lshl_b64 s[20:21], s[12:13], 18
	v_readlane_b32 s22, v251, 20
	v_addc_co_u32_e32 v9, vcc, 0, v3, vcc
	s_mov_b32 s13, 0x40000
	v_readlane_b32 s23, v251, 21
	s_add_u32 s20, s22, s20
	global_load_dwordx4 v[40:43], v[2:3], off
	global_load_dwordx4 v[44:47], v[8:9], off
	v_add_co_u32_e32 v10, vcc, s13, v2
	s_addc_u32 s21, s23, s21
	s_nop 0
	v_addc_co_u32_e32 v11, vcc, 0, v3, vcc
	global_load_dwordx4 v[48:51], v[10:11], off
	v_add_co_u32_e32 v12, vcc, s35, v2
	v_lshl_add_u64 v[14:15], s[20:21], 0, v[172:173]
	s_nop 0
	v_addc_co_u32_e32 v13, vcc, 0, v3, vcc
	global_load_dwordx4 v[56:59], v[14:15], off
	global_load_dwordx4 v[52:55], v[12:13], off
	v_add_co_u32_e32 v16, vcc, s5, v14
	v_add_u32_e32 v39, v19, v20
	s_nop 0
	v_addc_co_u32_e32 v17, vcc, 0, v15, vcc
	global_load_dwordx4 v[60:63], v[16:17], off
	global_load_dwordx4 v[64:67], v[2:3], off offset:128
	global_load_dwordx4 v[68:71], v[8:9], off offset:128
	global_load_dwordx4 v[72:75], v[10:11], off offset:128
	global_load_dwordx4 v[76:79], v[14:15], off offset:128
	global_load_dwordx4 v[80:83], v[12:13], off offset:128
	global_load_dwordx4 v[84:87], v[16:17], off offset:128
	s_barrier
	s_waitcnt vmcnt(11)
	ds_write_b128 v22, v[40:43]
	s_waitcnt vmcnt(10)
	ds_write_b128 v22, v[44:47] offset:10240
	s_waitcnt vmcnt(9)
	ds_write_b128 v22, v[48:51] offset:20480
	s_waitcnt vmcnt(8)
	ds_write_b128 v23, v[56:59]
	s_waitcnt vmcnt(7)
	ds_write_b128 v22, v[52:55] offset:30720
	s_waitcnt vmcnt(6)
	ds_write_b128 v25, v[60:63]
	s_waitcnt lgkmcnt(0)
	s_barrier
	global_load_dwordx4 v[42:45], v[2:3], off offset:256
	global_load_dwordx4 v[46:49], v[8:9], off offset:256
	global_load_dwordx4 v[50:53], v[10:11], off offset:256
	global_load_dwordx4 v[54:57], v[12:13], off offset:256
	global_load_dwordx4 v[58:61], v[14:15], off offset:256
	global_load_dwordx4 v[88:91], v[16:17], off offset:256
	v_add_u32_e32 v40, v19, v21
	ds_read_b128 v[92:95], v39
	ds_read_b128 v[96:99], v39 offset:2560
	ds_read_b128 v[100:103], v39 offset:5120
	ds_read_b128 v[104:107], v39 offset:7680
	ds_read_b128 v[108:111], v40 offset:40960
	ds_read_b128 v[112:115], v40 offset:43520
	ds_read_b128 v[116:119], v40 offset:46080
	ds_read_b128 v[120:123], v40 offset:48640
	ds_read_b128 v[124:127], v30 offset:64
	ds_read_b128 v[128:131], v30 offset:2624
	ds_read_b128 v[132:135], v30 offset:5184
	ds_read_b128 v[136:139], v30 offset:7744
	ds_read_b128 v[140:143], v31 offset:41024
	ds_read_b128 v[144:147], v31 offset:43584
	ds_read_b128 v[152:155], v31 offset:46144
	ds_read_b128 v[156:159], v31 offset:48704
	s_waitcnt lgkmcnt(11)
	v_mfma_f32_16x16x32_bf16 v[174:177], v[108:111], v[92:95], 0
	s_waitcnt vmcnt(11)
	ds_write_b128 v22, v[64:67] offset:61440
	s_waitcnt vmcnt(8)
	ds_write_b128 v23, v[76:79] offset:61440
	s_waitcnt lgkmcnt(12)
	v_mfma_f32_16x16x32_bf16 v[178:181], v[112:115], v[92:95], 0
	s_waitcnt lgkmcnt(11)
	v_mfma_f32_16x16x32_bf16 v[182:185], v[116:119], v[92:95], 0
	s_waitcnt lgkmcnt(10)
	v_mfma_f32_16x16x32_bf16 v[62:65], v[120:123], v[92:95], 0
	v_mfma_f32_16x16x32_bf16 v[76:79], v[108:111], v[96:99], 0
	ds_write_b128 v24, v[68:71] offset:61440
	s_waitcnt vmcnt(6)
	ds_write_b128 v25, v[84:87] offset:61440
	v_mfma_f32_16x16x32_bf16 v[92:95], v[112:115], v[96:99], 0
	v_mfma_f32_16x16x32_bf16 v[186:189], v[116:119], v[96:99], 0
	v_mfma_f32_16x16x32_bf16 v[66:69], v[120:123], v[96:99], 0
	v_mfma_f32_16x16x32_bf16 v[84:87], v[108:111], v[100:103], 0
	ds_write_b128 v26, v[72:75] offset:61440
	v_mfma_f32_16x16x32_bf16 v[96:99], v[112:115], v[100:103], 0
	v_mfma_f32_16x16x32_bf16 v[190:193], v[116:119], v[100:103], 0
	v_mfma_f32_16x16x32_bf16 v[70:73], v[120:123], v[100:103], 0
	v_mfma_f32_16x16x32_bf16 v[100:103], v[108:111], v[104:107], 0
	ds_write_b128 v27, v[80:83] offset:61440
	v_mfma_f32_16x16x32_bf16 v[108:111], v[112:115], v[104:107], 0
	v_mfma_f32_16x16x32_bf16 v[112:115], v[116:119], v[104:107], 0
	v_mfma_f32_16x16x32_bf16 v[80:83], v[120:123], v[104:107], 0
	s_waitcnt lgkmcnt(0)
	s_barrier
	ds_read_b128 v[104:107], v39 offset:61440
	ds_read_b128 v[116:119], v39 offset:64000
	ds_read_b128 v[120:123], v32 offset:5120
	ds_read_b128 v[194:197], v32 offset:7680
	ds_read_b128 v[198:201], v33
	ds_read_b128 v[202:205], v33 offset:2560
	ds_read_b128 v[206:209], v33 offset:5120
	ds_read_b128 v[210:213], v33 offset:7680
	v_mfma_f32_16x16x32_bf16 v[174:177], v[140:143], v[124:127], v[174:177]
	v_mfma_f32_16x16x32_bf16 v[178:181], v[144:147], v[124:127], v[178:181]
	v_mfma_f32_16x16x32_bf16 v[182:185], v[152:155], v[124:127], v[182:185]
	v_mfma_f32_16x16x32_bf16 v[62:65], v[156:159], v[124:127], v[62:65]
	v_mfma_f32_16x16x32_bf16 v[74:77], v[140:143], v[128:131], v[76:79]
	v_mfma_f32_16x16x32_bf16 v[92:95], v[144:147], v[128:131], v[92:95]
	v_mfma_f32_16x16x32_bf16 v[124:127], v[152:155], v[128:131], v[186:189]
	v_mfma_f32_16x16x32_bf16 v[66:69], v[156:159], v[128:131], v[66:69]
	v_mfma_f32_16x16x32_bf16 v[84:87], v[140:143], v[132:135], v[84:87]
	v_mfma_f32_16x16x32_bf16 v[96:99], v[144:147], v[132:135], v[96:99]
	v_mfma_f32_16x16x32_bf16 v[128:131], v[152:155], v[132:135], v[190:193]
	v_mfma_f32_16x16x32_bf16 v[70:73], v[156:159], v[132:135], v[70:73]
	v_mfma_f32_16x16x32_bf16 v[100:103], v[140:143], v[136:139], v[100:103]
	v_mfma_f32_16x16x32_bf16 v[108:111], v[144:147], v[136:139], v[108:111]
	v_mfma_f32_16x16x32_bf16 v[112:115], v[152:155], v[136:139], v[112:115]
	v_mfma_f32_16x16x32_bf16 v[78:81], v[156:159], v[136:139], v[80:83]
	global_load_dwordx4 v[132:135], v[2:3], off offset:384
	global_load_dwordx4 v[136:139], v[8:9], off offset:384
	global_load_dwordx4 v[140:143], v[10:11], off offset:384
	global_load_dwordx4 v[144:147], v[12:13], off offset:384
	global_load_dwordx4 v[152:155], v[14:15], off offset:384
	global_load_dwordx4 v[156:159], v[16:17], off offset:384
	v_add_u32_e32 v41, v28, v18
	ds_read_b128 v[186:189], v30 offset:61504
	ds_read_b128 v[190:193], v30 offset:64064
	ds_read_b128 v[214:217], v34 offset:64
	ds_read_b128 v[218:221], v35 offset:64
	ds_read_b128 v[222:225], v41 offset:64
	ds_read_b128 v[226:229], v36 offset:64
	ds_read_b128 v[230:233], v37 offset:64
	ds_read_b128 v[234:237], v38 offset:64
	s_waitcnt lgkmcnt(11)
;     ...
;   for (int k0 = 0; k0 < K; k0 += 128) {
;     G_READ(fa1, fb1, 0, 32);
;     if (k0 + 128 < K) G_LOAD(ra0, rb0, k0 + 128);
;     __builtin_amdgcn_sched_barrier(0);
;     G_MFMA_ST(fa0, fb0, ra1, rb1, 1);
;     __syncthreads();
;     G_READ(fa0, fb0, 1, 0);
;     __builtin_amdgcn_sched_barrier(0);
;     G_MFMA(fa1, fb1);
;     __builtin_amdgcn_sched_barrier(0);
;     G_READ(fa1, fb1, 1, 32);
;     if (k0 + 192 < K) G_LOAD(ra1, rb1, k0 + 192);
;     __builtin_amdgcn_sched_barrier(0);
;     if (k0 + 128 < K) {
;       G_MFMA_ST(fa0, fb0, ra0, rb0, 0);
;       __syncthreads();
;       G_READ(fa0, fb0, 0, 0);
;     } else {
;       G_MFMA(fa0, fb0);
;     }
;     __builtin_amdgcn_sched_barrier(0);
;     G_MFMA(fa1, fb1);
;     __builtin_amdgcn_sched_barrier(0);
;   }
	v_mfma_f32_16x16x32_bf16 v[174:177], v[198:201], v[104:107], v[174:177]
	s_waitcnt vmcnt(11)
	ds_write_b128 v22, v[42:45]
	s_waitcnt vmcnt(7)
	ds_write_b128 v23, v[58:61]
	s_waitcnt lgkmcnt(12)
	v_mfma_f32_16x16x32_bf16 v[178:181], v[202:205], v[104:107], v[178:181]
	s_waitcnt lgkmcnt(11)
	v_mfma_f32_16x16x32_bf16 v[182:185], v[206:209], v[104:107], v[182:185]
	s_waitcnt lgkmcnt(10)
	v_mfma_f32_16x16x32_bf16 v[42:45], v[210:213], v[104:107], v[62:65]
	v_mfma_f32_16x16x32_bf16 v[58:61], v[198:201], v[116:119], v[74:77]
	ds_write_b128 v22, v[46:49] offset:10240
	s_waitcnt vmcnt(6)
	ds_write_b128 v25, v[88:91]
	v_mfma_f32_16x16x32_bf16 v[62:65], v[202:205], v[116:119], v[92:95]
	v_mfma_f32_16x16x32_bf16 v[74:77], v[206:209], v[116:119], v[124:127]
	v_mfma_f32_16x16x32_bf16 v[46:49], v[210:213], v[116:119], v[66:69]
	v_mfma_f32_16x16x32_bf16 v[66:69], v[198:201], v[120:123], v[84:87]
	ds_write_b128 v22, v[50:53] offset:20480
	v_mfma_f32_16x16x32_bf16 v[82:85], v[202:205], v[120:123], v[96:99]
	v_mfma_f32_16x16x32_bf16 v[86:89], v[206:209], v[120:123], v[128:131]
	v_mfma_f32_16x16x32_bf16 v[50:53], v[210:213], v[120:123], v[70:73]
	v_mfma_f32_16x16x32_bf16 v[70:73], v[198:201], v[194:197], v[100:103]
	ds_write_b128 v22, v[54:57] offset:30720
	v_mfma_f32_16x16x32_bf16 v[90:93], v[202:205], v[194:197], v[108:111]
	v_mfma_f32_16x16x32_bf16 v[94:97], v[206:209], v[194:197], v[112:115]
	v_mfma_f32_16x16x32_bf16 v[54:57], v[210:213], v[194:197], v[78:81]
	s_waitcnt lgkmcnt(0)
	s_barrier
	s_nop 0
	ds_read_b128 v[78:81], v39
	ds_read_b128 v[98:101], v39 offset:2560
	ds_read_b128 v[102:105], v39 offset:5120
	ds_read_b128 v[106:109], v39 offset:7680
	ds_read_b128 v[110:113], v40 offset:40960
	ds_read_b128 v[114:117], v40 offset:43520
	ds_read_b128 v[118:121], v40 offset:46080
	ds_read_b128 v[122:125], v40 offset:48640
	v_mfma_f32_16x16x32_bf16 v[126:129], v[222:225], v[186:189], v[174:177]
	v_mfma_f32_16x16x32_bf16 v[174:177], v[226:229], v[186:189], v[178:181]
	v_mfma_f32_16x16x32_bf16 v[178:181], v[230:233], v[186:189], v[182:185]
	v_mfma_f32_16x16x32_bf16 v[42:45], v[234:237], v[186:189], v[42:45]
	v_mfma_f32_16x16x32_bf16 v[58:61], v[222:225], v[190:193], v[58:61]
	v_mfma_f32_16x16x32_bf16 v[62:65], v[226:229], v[190:193], v[62:65]
	v_mfma_f32_16x16x32_bf16 v[74:77], v[230:233], v[190:193], v[74:77]
	v_mfma_f32_16x16x32_bf16 v[46:49], v[234:237], v[190:193], v[46:49]
	v_mfma_f32_16x16x32_bf16 v[66:69], v[222:225], v[214:217], v[66:69]
	v_mfma_f32_16x16x32_bf16 v[82:85], v[226:229], v[214:217], v[82:85]
	v_mfma_f32_16x16x32_bf16 v[86:89], v[230:233], v[214:217], v[86:89]
	v_mfma_f32_16x16x32_bf16 v[50:53], v[234:237], v[214:217], v[50:53]
	v_mfma_f32_16x16x32_bf16 v[70:73], v[222:225], v[218:221], v[70:73]
	v_mfma_f32_16x16x32_bf16 v[90:93], v[226:229], v[218:221], v[90:93]
	v_mfma_f32_16x16x32_bf16 v[94:97], v[230:233], v[218:221], v[94:97]
	v_mfma_f32_16x16x32_bf16 v[54:57], v[234:237], v[218:221], v[54:57]
	global_load_dwordx4 v[182:185], v[2:3], off offset:512
	global_load_dwordx4 v[186:189], v[8:9], off offset:512
	global_load_dwordx4 v[190:193], v[10:11], off offset:512
	global_load_dwordx4 v[194:197], v[12:13], off offset:512
	global_load_dwordx4 v[198:201], v[14:15], off offset:512
	global_load_dwordx4 v[202:205], v[16:17], off offset:512
	ds_read_b128 v[206:209], v30 offset:64
	ds_read_b128 v[210:213], v30 offset:2624
	ds_read_b128 v[214:217], v30 offset:5184
	ds_read_b128 v[218:221], v30 offset:7744
	ds_read_b128 v[222:225], v31 offset:41024
	ds_read_b128 v[226:229], v31 offset:43584
	ds_read_b128 v[230:233], v31 offset:46144
	ds_read_b128 v[234:237], v31 offset:48704
	s_waitcnt lgkmcnt(11)
	v_mfma_f32_16x16x32_bf16 v[126:129], v[110:113], v[78:81], v[126:129]
	s_waitcnt vmcnt(11)
	ds_write_b128 v22, v[132:135] offset:61440
	s_waitcnt vmcnt(7)
	ds_write_b128 v23, v[152:155] offset:61440
	s_waitcnt lgkmcnt(12)
	v_mfma_f32_16x16x32_bf16 v[174:177], v[114:117], v[78:81], v[174:177]
	s_waitcnt lgkmcnt(11)
	v_mfma_f32_16x16x32_bf16 v[178:181], v[118:121], v[78:81], v[178:181]
	s_waitcnt lgkmcnt(10)
	v_mfma_f32_16x16x32_bf16 v[42:45], v[122:125], v[78:81], v[42:45]
	v_mfma_f32_16x16x32_bf16 v[58:61], v[110:113], v[98:101], v[58:61]
	ds_write_b128 v24, v[136:139] offset:61440
	s_waitcnt vmcnt(6)
	ds_write_b128 v25, v[156:159] offset:61440
	v_mfma_f32_16x16x32_bf16 v[62:65], v[114:117], v[98:101], v[62:65]
	v_mfma_f32_16x16x32_bf16 v[74:77], v[118:121], v[98:101], v[74:77]
	v_mfma_f32_16x16x32_bf16 v[46:49], v[122:125], v[98:101], v[46:49]
	v_mfma_f32_16x16x32_bf16 v[66:69], v[110:113], v[102:105], v[66:69]
	ds_write_b128 v26, v[140:143] offset:61440
	v_mfma_f32_16x16x32_bf16 v[78:81], v[114:117], v[102:105], v[82:85]
	v_mfma_f32_16x16x32_bf16 v[82:85], v[118:121], v[102:105], v[86:89]
	v_mfma_f32_16x16x32_bf16 v[50:53], v[122:125], v[102:105], v[50:53]
	v_mfma_f32_16x16x32_bf16 v[70:73], v[110:113], v[106:109], v[70:73]
	ds_write_b128 v27, v[144:147] offset:61440
	v_mfma_f32_16x16x32_bf16 v[86:89], v[114:117], v[106:109], v[90:93]
	v_mfma_f32_16x16x32_bf16 v[90:93], v[118:121], v[106:109], v[94:97]
	v_mfma_f32_16x16x32_bf16 v[54:57], v[122:125], v[106:109], v[54:57]
	s_waitcnt lgkmcnt(0)
	s_barrier
;     ...
;   for (int k0 = 0; k0 < K; k0 += 128) {
;     G_READ(fa1, fb1, 0, 32);
;     if (k0 + 128 < K) G_LOAD(ra0, rb0, k0 + 128);
;     __builtin_amdgcn_sched_barrier(0);
;     G_MFMA_ST(fa0, fb0, ra1, rb1, 1);
;     __syncthreads();
;     G_READ(fa0, fb0, 1, 0);
;     __builtin_amdgcn_sched_barrier(0);
;     G_MFMA(fa1, fb1);
;     __builtin_amdgcn_sched_barrier(0);
;     G_READ(fa1, fb1, 1, 32);
;     if (k0 + 192 < K) G_LOAD(ra1, rb1, k0 + 192);
;     __builtin_amdgcn_sched_barrier(0);
;     if (k0 + 128 < K) {
;       G_MFMA_ST(fa0, fb0, ra0, rb0, 0);
;       __syncthreads();
;       G_READ(fa0, fb0, 0, 0);
;     } else {
;       G_MFMA(fa0, fb0);
;     }
;     __builtin_amdgcn_sched_barrier(0);
;     G_MFMA(fa1, fb1);
;     __builtin_amdgcn_sched_barrier(0);
;   }
	ds_read_b128 v[94:97], v39 offset:61440
	ds_read_b128 v[98:101], v39 offset:64000
	ds_read_b128 v[102:105], v32 offset:5120
	ds_read_b128 v[106:109], v32 offset:7680
	ds_read_b128 v[110:113], v33
	ds_read_b128 v[114:117], v33 offset:2560
	ds_read_b128 v[118:121], v33 offset:5120
	ds_read_b128 v[122:125], v33 offset:7680
	v_mfma_f32_16x16x32_bf16 v[126:129], v[222:225], v[206:209], v[126:129]
	v_mfma_f32_16x16x32_bf16 v[130:133], v[226:229], v[206:209], v[174:177]
	v_mfma_f32_16x16x32_bf16 v[134:137], v[230:233], v[206:209], v[178:181]
	v_mfma_f32_16x16x32_bf16 v[42:45], v[234:237], v[206:209], v[42:45]
	v_mfma_f32_16x16x32_bf16 v[58:61], v[222:225], v[210:213], v[58:61]
	v_mfma_f32_16x16x32_bf16 v[62:65], v[226:229], v[210:213], v[62:65]
	v_mfma_f32_16x16x32_bf16 v[74:77], v[230:233], v[210:213], v[74:77]
	v_mfma_f32_16x16x32_bf16 v[46:49], v[234:237], v[210:213], v[46:49]
	v_mfma_f32_16x16x32_bf16 v[66:69], v[222:225], v[214:217], v[66:69]
	v_mfma_f32_16x16x32_bf16 v[78:81], v[226:229], v[214:217], v[78:81]
	v_mfma_f32_16x16x32_bf16 v[82:85], v[230:233], v[214:217], v[82:85]
	v_mfma_f32_16x16x32_bf16 v[50:53], v[234:237], v[214:217], v[50:53]
	v_mfma_f32_16x16x32_bf16 v[70:73], v[222:225], v[218:221], v[70:73]
	v_mfma_f32_16x16x32_bf16 v[86:89], v[226:229], v[218:221], v[86:89]
	v_mfma_f32_16x16x32_bf16 v[90:93], v[230:233], v[218:221], v[90:93]
	v_mfma_f32_16x16x32_bf16 v[54:57], v[234:237], v[218:221], v[54:57]
	global_load_dwordx4 v[138:141], v[2:3], off offset:640
	global_load_dwordx4 v[142:145], v[8:9], off offset:640
	global_load_dwordx4 v[152:155], v[10:11], off offset:640
	global_load_dwordx4 v[156:159], v[12:13], off offset:640
	global_load_dwordx4 v[174:177], v[14:15], off offset:640
	global_load_dwordx4 v[178:181], v[16:17], off offset:640
	ds_read_b128 v[206:209], v30 offset:61504
	ds_read_b128 v[210:213], v30 offset:64064
	ds_read_b128 v[214:217], v34 offset:64
	ds_read_b128 v[218:221], v35 offset:64
	ds_read_b128 v[222:225], v41 offset:64
	ds_read_b128 v[226:229], v36 offset:64
	ds_read_b128 v[230:233], v37 offset:64
	ds_read_b128 v[234:237], v38 offset:64
	s_waitcnt lgkmcnt(11)
	v_mfma_f32_16x16x32_bf16 v[126:129], v[110:113], v[94:97], v[126:129]
	s_waitcnt vmcnt(11)
	ds_write_b128 v22, v[182:185]
	s_waitcnt vmcnt(7)
	ds_write_b128 v23, v[198:201]
	s_waitcnt lgkmcnt(12)
	v_mfma_f32_16x16x32_bf16 v[130:133], v[114:117], v[94:97], v[130:133]
	s_waitcnt lgkmcnt(11)
	v_mfma_f32_16x16x32_bf16 v[134:137], v[118:121], v[94:97], v[134:137]
	s_waitcnt lgkmcnt(10)
	v_mfma_f32_16x16x32_bf16 v[42:45], v[122:125], v[94:97], v[42:45]
	v_mfma_f32_16x16x32_bf16 v[58:61], v[110:113], v[98:101], v[58:61]
	ds_write_b128 v22, v[186:189] offset:10240
	s_waitcnt vmcnt(6)
	ds_write_b128 v25, v[202:205]
	v_mfma_f32_16x16x32_bf16 v[62:65], v[114:117], v[98:101], v[62:65]
	v_mfma_f32_16x16x32_bf16 v[74:77], v[118:121], v[98:101], v[74:77]
	v_mfma_f32_16x16x32_bf16 v[46:49], v[122:125], v[98:101], v[46:49]
	v_mfma_f32_16x16x32_bf16 v[66:69], v[110:113], v[102:105], v[66:69]
	ds_write_b128 v22, v[190:193] offset:20480
	v_mfma_f32_16x16x32_bf16 v[78:81], v[114:117], v[102:105], v[78:81]
	v_mfma_f32_16x16x32_bf16 v[82:85], v[118:121], v[102:105], v[82:85]
	v_mfma_f32_16x16x32_bf16 v[50:53], v[122:125], v[102:105], v[50:53]
	v_mfma_f32_16x16x32_bf16 v[70:73], v[110:113], v[106:109], v[70:73]
	ds_write_b128 v22, v[194:197] offset:30720
	v_mfma_f32_16x16x32_bf16 v[86:89], v[114:117], v[106:109], v[86:89]
	v_mfma_f32_16x16x32_bf16 v[90:93], v[118:121], v[106:109], v[90:93]
	v_mfma_f32_16x16x32_bf16 v[54:57], v[122:125], v[106:109], v[54:57]
	s_waitcnt lgkmcnt(0)
	s_barrier
	ds_read_b128 v[94:97], v39
	ds_read_b128 v[98:101], v39 offset:2560
	ds_read_b128 v[102:105], v39 offset:5120
	ds_read_b128 v[106:109], v39 offset:7680
	ds_read_b128 v[110:113], v40 offset:40960
	ds_read_b128 v[114:117], v40 offset:43520
	ds_read_b128 v[118:121], v40 offset:46080
	ds_read_b128 v[122:125], v40 offset:48640
	v_mfma_f32_16x16x32_bf16 v[126:129], v[222:225], v[206:209], v[126:129]
	v_mfma_f32_16x16x32_bf16 v[130:133], v[226:229], v[206:209], v[130:133]
	v_mfma_f32_16x16x32_bf16 v[134:137], v[230:233], v[206:209], v[134:137]
	v_mfma_f32_16x16x32_bf16 v[42:45], v[234:237], v[206:209], v[42:45]
	v_mfma_f32_16x16x32_bf16 v[58:61], v[222:225], v[210:213], v[58:61]
	v_mfma_f32_16x16x32_bf16 v[62:65], v[226:229], v[210:213], v[62:65]
	v_mfma_f32_16x16x32_bf16 v[74:77], v[230:233], v[210:213], v[74:77]
	v_mfma_f32_16x16x32_bf16 v[46:49], v[234:237], v[210:213], v[46:49]
	v_mfma_f32_16x16x32_bf16 v[66:69], v[222:225], v[214:217], v[66:69]
	v_mfma_f32_16x16x32_bf16 v[78:81], v[226:229], v[214:217], v[78:81]
	v_mfma_f32_16x16x32_bf16 v[82:85], v[230:233], v[214:217], v[82:85]
	v_mfma_f32_16x16x32_bf16 v[50:53], v[234:237], v[214:217], v[50:53]
	v_mfma_f32_16x16x32_bf16 v[70:73], v[222:225], v[218:221], v[70:73]
	v_mfma_f32_16x16x32_bf16 v[86:89], v[226:229], v[218:221], v[86:89]
	v_mfma_f32_16x16x32_bf16 v[90:93], v[230:233], v[218:221], v[90:93]
	v_mfma_f32_16x16x32_bf16 v[54:57], v[234:237], v[218:221], v[54:57]
	global_load_dwordx4 v[182:185], v[2:3], off offset:768
	global_load_dwordx4 v[186:189], v[8:9], off offset:768
	global_load_dwordx4 v[190:193], v[10:11], off offset:768
	global_load_dwordx4 v[194:197], v[12:13], off offset:768
	global_load_dwordx4 v[198:201], v[14:15], off offset:768
	global_load_dwordx4 v[202:205], v[16:17], off offset:768
	ds_read_b128 v[206:209], v30 offset:64
	ds_read_b128 v[210:213], v30 offset:2624
	ds_read_b128 v[214:217], v30 offset:5184
	ds_read_b128 v[218:221], v30 offset:7744
	ds_read_b128 v[222:225], v31 offset:41024
	ds_read_b128 v[226:229], v31 offset:43584
	ds_read_b128 v[230:233], v31 offset:46144
	ds_read_b128 v[234:237], v31 offset:48704
	s_waitcnt lgkmcnt(11)
;     ...
;   for (int k0 = 0; k0 < K; k0 += 128) {
;     G_READ(fa1, fb1, 0, 32);
;     if (k0 + 128 < K) G_LOAD(ra0, rb0, k0 + 128);
;     __builtin_amdgcn_sched_barrier(0);
;     G_MFMA_ST(fa0, fb0, ra1, rb1, 1);
;     __syncthreads();
;     G_READ(fa0, fb0, 1, 0);
;     __builtin_amdgcn_sched_barrier(0);
;     G_MFMA(fa1, fb1);
;     __builtin_amdgcn_sched_barrier(0);
;     G_READ(fa1, fb1, 1, 32);
;     if (k0 + 192 < K) G_LOAD(ra1, rb1, k0 + 192);
;     __builtin_amdgcn_sched_barrier(0);
;     if (k0 + 128 < K) {
;       G_MFMA_ST(fa0, fb0, ra0, rb0, 0);
;       __syncthreads();
;       G_READ(fa0, fb0, 0, 0);
;     } else {
;       G_MFMA(fa0, fb0);
;     }
;     __builtin_amdgcn_sched_barrier(0);
;     G_MFMA(fa1, fb1);
;     __builtin_amdgcn_sched_barrier(0);
;   }
	v_mfma_f32_16x16x32_bf16 v[126:129], v[110:113], v[94:97], v[126:129]
	s_waitcnt vmcnt(11)
	ds_write_b128 v22, v[138:141] offset:61440
	s_waitcnt vmcnt(7)
	ds_write_b128 v23, v[174:177] offset:61440
	s_waitcnt lgkmcnt(12)
	v_mfma_f32_16x16x32_bf16 v[130:133], v[114:117], v[94:97], v[130:133]
	s_waitcnt lgkmcnt(11)
	v_mfma_f32_16x16x32_bf16 v[134:137], v[118:121], v[94:97], v[134:137]
	s_waitcnt lgkmcnt(10)
	v_mfma_f32_16x16x32_bf16 v[42:45], v[122:125], v[94:97], v[42:45]
	v_mfma_f32_16x16x32_bf16 v[58:61], v[110:113], v[98:101], v[58:61]
	ds_write_b128 v24, v[142:145] offset:61440
	s_waitcnt vmcnt(6)
	ds_write_b128 v25, v[178:181] offset:61440
	v_mfma_f32_16x16x32_bf16 v[62:65], v[114:117], v[98:101], v[62:65]
	v_mfma_f32_16x16x32_bf16 v[74:77], v[118:121], v[98:101], v[74:77]
	v_mfma_f32_16x16x32_bf16 v[46:49], v[122:125], v[98:101], v[46:49]
	v_mfma_f32_16x16x32_bf16 v[66:69], v[110:113], v[102:105], v[66:69]
	ds_write_b128 v26, v[152:155] offset:61440
	v_mfma_f32_16x16x32_bf16 v[78:81], v[114:117], v[102:105], v[78:81]
	v_mfma_f32_16x16x32_bf16 v[82:85], v[118:121], v[102:105], v[82:85]
	v_mfma_f32_16x16x32_bf16 v[50:53], v[122:125], v[102:105], v[50:53]
	v_mfma_f32_16x16x32_bf16 v[70:73], v[110:113], v[106:109], v[70:73]
	ds_write_b128 v27, v[156:159] offset:61440
	v_mfma_f32_16x16x32_bf16 v[86:89], v[114:117], v[106:109], v[86:89]
	v_mfma_f32_16x16x32_bf16 v[90:93], v[118:121], v[106:109], v[90:93]
	v_mfma_f32_16x16x32_bf16 v[54:57], v[122:125], v[106:109], v[54:57]
	s_waitcnt lgkmcnt(0)
	s_barrier
	ds_read_b128 v[94:97], v39 offset:61440
	ds_read_b128 v[98:101], v39 offset:64000
	ds_read_b128 v[102:105], v32 offset:5120
	ds_read_b128 v[106:109], v32 offset:7680
	ds_read_b128 v[110:113], v33
	ds_read_b128 v[114:117], v33 offset:2560
	ds_read_b128 v[118:121], v33 offset:5120
	ds_read_b128 v[122:125], v33 offset:7680
	v_mfma_f32_16x16x32_bf16 v[126:129], v[222:225], v[206:209], v[126:129]
	v_mfma_f32_16x16x32_bf16 v[130:133], v[226:229], v[206:209], v[130:133]
	v_mfma_f32_16x16x32_bf16 v[134:137], v[230:233], v[206:209], v[134:137]
	v_mfma_f32_16x16x32_bf16 v[42:45], v[234:237], v[206:209], v[42:45]
	v_mfma_f32_16x16x32_bf16 v[58:61], v[222:225], v[210:213], v[58:61]
	v_mfma_f32_16x16x32_bf16 v[62:65], v[226:229], v[210:213], v[62:65]
	v_mfma_f32_16x16x32_bf16 v[74:77], v[230:233], v[210:213], v[74:77]
	v_mfma_f32_16x16x32_bf16 v[46:49], v[234:237], v[210:213], v[46:49]
	v_mfma_f32_16x16x32_bf16 v[66:69], v[222:225], v[214:217], v[66:69]
	v_mfma_f32_16x16x32_bf16 v[78:81], v[226:229], v[214:217], v[78:81]
	v_mfma_f32_16x16x32_bf16 v[82:85], v[230:233], v[214:217], v[82:85]
	v_mfma_f32_16x16x32_bf16 v[50:53], v[234:237], v[214:217], v[50:53]
	v_mfma_f32_16x16x32_bf16 v[70:73], v[222:225], v[218:221], v[70:73]
	v_mfma_f32_16x16x32_bf16 v[86:89], v[226:229], v[218:221], v[86:89]
	v_mfma_f32_16x16x32_bf16 v[90:93], v[230:233], v[218:221], v[90:93]
	v_mfma_f32_16x16x32_bf16 v[54:57], v[234:237], v[218:221], v[54:57]
	global_load_dwordx4 v[138:141], v[2:3], off offset:896
	global_load_dwordx4 v[142:145], v[8:9], off offset:896
	global_load_dwordx4 v[152:155], v[10:11], off offset:896
	global_load_dwordx4 v[156:159], v[12:13], off offset:896
	global_load_dwordx4 v[174:177], v[14:15], off offset:896
	global_load_dwordx4 v[178:181], v[16:17], off offset:896
	ds_read_b128 v[206:209], v30 offset:61504
	ds_read_b128 v[210:213], v30 offset:64064
	ds_read_b128 v[214:217], v34 offset:64
	ds_read_b128 v[218:221], v35 offset:64
	ds_read_b128 v[222:225], v41 offset:64
	ds_read_b128 v[226:229], v36 offset:64
	ds_read_b128 v[230:233], v37 offset:64
	ds_read_b128 v[234:237], v38 offset:64
	s_waitcnt lgkmcnt(11)
	v_mfma_f32_16x16x32_bf16 v[126:129], v[110:113], v[94:97], v[126:129]
	s_waitcnt vmcnt(11)
	ds_write_b128 v22, v[182:185]
	s_waitcnt vmcnt(7)
	ds_write_b128 v23, v[198:201]
	s_waitcnt lgkmcnt(12)
	v_mfma_f32_16x16x32_bf16 v[130:133], v[114:117], v[94:97], v[130:133]
	s_waitcnt lgkmcnt(11)
	v_mfma_f32_16x16x32_bf16 v[134:137], v[118:121], v[94:97], v[134:137]
	s_waitcnt lgkmcnt(10)
	v_mfma_f32_16x16x32_bf16 v[42:45], v[122:125], v[94:97], v[42:45]
	v_mfma_f32_16x16x32_bf16 v[58:61], v[110:113], v[98:101], v[58:61]
	ds_write_b128 v22, v[186:189] offset:10240
	s_waitcnt vmcnt(6)
	ds_write_b128 v25, v[202:205]
	v_mfma_f32_16x16x32_bf16 v[62:65], v[114:117], v[98:101], v[62:65]
	v_mfma_f32_16x16x32_bf16 v[74:77], v[118:121], v[98:101], v[74:77]
	v_mfma_f32_16x16x32_bf16 v[46:49], v[122:125], v[98:101], v[46:49]
	v_mfma_f32_16x16x32_bf16 v[66:69], v[110:113], v[102:105], v[66:69]
	ds_write_b128 v22, v[190:193] offset:20480
	v_mfma_f32_16x16x32_bf16 v[78:81], v[114:117], v[102:105], v[78:81]
	v_mfma_f32_16x16x32_bf16 v[82:85], v[118:121], v[102:105], v[82:85]
	v_mfma_f32_16x16x32_bf16 v[50:53], v[122:125], v[102:105], v[50:53]
	v_mfma_f32_16x16x32_bf16 v[70:73], v[110:113], v[106:109], v[70:73]
	ds_write_b128 v22, v[194:197] offset:30720
	v_mfma_f32_16x16x32_bf16 v[86:89], v[114:117], v[106:109], v[86:89]
	v_mfma_f32_16x16x32_bf16 v[90:93], v[118:121], v[106:109], v[90:93]
	v_mfma_f32_16x16x32_bf16 v[54:57], v[122:125], v[106:109], v[54:57]
	s_waitcnt lgkmcnt(0)
	s_barrier
;     ...
;   for (int k0 = 0; k0 < K; k0 += 128) {
;     G_READ(fa1, fb1, 0, 32);
;     if (k0 + 128 < K) G_LOAD(ra0, rb0, k0 + 128);
;     __builtin_amdgcn_sched_barrier(0);
;     G_MFMA_ST(fa0, fb0, ra1, rb1, 1);
;     __syncthreads();
;     G_READ(fa0, fb0, 1, 0);
;     __builtin_amdgcn_sched_barrier(0);
;     G_MFMA(fa1, fb1);
;     __builtin_amdgcn_sched_barrier(0);
;     G_READ(fa1, fb1, 1, 32);
;     if (k0 + 192 < K) G_LOAD(ra1, rb1, k0 + 192);
;     __builtin_amdgcn_sched_barrier(0);
;     if (k0 + 128 < K) {
;       G_MFMA_ST(fa0, fb0, ra0, rb0, 0);
;       __syncthreads();
;       G_READ(fa0, fb0, 0, 0);
;     } else {
;       G_MFMA(fa0, fb0);
;     }
;     __builtin_amdgcn_sched_barrier(0);
;     G_MFMA(fa1, fb1);
;     __builtin_amdgcn_sched_barrier(0);
;   }
	ds_read_b128 v[94:97], v39
	ds_read_b128 v[98:101], v39 offset:2560
	ds_read_b128 v[102:105], v39 offset:5120
	ds_read_b128 v[106:109], v39 offset:7680
	ds_read_b128 v[110:113], v40 offset:40960
	ds_read_b128 v[114:117], v40 offset:43520
	ds_read_b128 v[118:121], v40 offset:46080
	ds_read_b128 v[122:125], v40 offset:48640
	v_mfma_f32_16x16x32_bf16 v[126:129], v[222:225], v[206:209], v[126:129]
	v_mfma_f32_16x16x32_bf16 v[130:133], v[226:229], v[206:209], v[130:133]
	v_mfma_f32_16x16x32_bf16 v[134:137], v[230:233], v[206:209], v[134:137]
	v_mfma_f32_16x16x32_bf16 v[42:45], v[234:237], v[206:209], v[42:45]
	v_mfma_f32_16x16x32_bf16 v[58:61], v[222:225], v[210:213], v[58:61]
	v_mfma_f32_16x16x32_bf16 v[62:65], v[226:229], v[210:213], v[62:65]
	v_mfma_f32_16x16x32_bf16 v[74:77], v[230:233], v[210:213], v[74:77]
	v_mfma_f32_16x16x32_bf16 v[46:49], v[234:237], v[210:213], v[46:49]
	v_mfma_f32_16x16x32_bf16 v[66:69], v[222:225], v[214:217], v[66:69]
	v_mfma_f32_16x16x32_bf16 v[78:81], v[226:229], v[214:217], v[78:81]
	v_mfma_f32_16x16x32_bf16 v[82:85], v[230:233], v[214:217], v[82:85]
	v_mfma_f32_16x16x32_bf16 v[50:53], v[234:237], v[214:217], v[50:53]
	v_mfma_f32_16x16x32_bf16 v[70:73], v[222:225], v[218:221], v[70:73]
	v_mfma_f32_16x16x32_bf16 v[86:89], v[226:229], v[218:221], v[86:89]
	v_mfma_f32_16x16x32_bf16 v[90:93], v[230:233], v[218:221], v[90:93]
	v_mfma_f32_16x16x32_bf16 v[54:57], v[234:237], v[218:221], v[54:57]
	global_load_dwordx4 v[182:185], v[2:3], off offset:1024
	global_load_dwordx4 v[186:189], v[8:9], off offset:1024
	global_load_dwordx4 v[190:193], v[10:11], off offset:1024
	global_load_dwordx4 v[194:197], v[12:13], off offset:1024
	global_load_dwordx4 v[198:201], v[14:15], off offset:1024
	global_load_dwordx4 v[202:205], v[16:17], off offset:1024
	ds_read_b128 v[206:209], v30 offset:64
	ds_read_b128 v[210:213], v30 offset:2624
	ds_read_b128 v[214:217], v30 offset:5184
	ds_read_b128 v[218:221], v30 offset:7744
	ds_read_b128 v[222:225], v31 offset:41024
	ds_read_b128 v[226:229], v31 offset:43584
	ds_read_b128 v[230:233], v31 offset:46144
	ds_read_b128 v[234:237], v31 offset:48704
	s_waitcnt lgkmcnt(11)
	v_mfma_f32_16x16x32_bf16 v[126:129], v[110:113], v[94:97], v[126:129]
	s_waitcnt vmcnt(11)
	ds_write_b128 v22, v[138:141] offset:61440
	s_waitcnt vmcnt(7)
	ds_write_b128 v23, v[174:177] offset:61440
	s_waitcnt lgkmcnt(12)
	v_mfma_f32_16x16x32_bf16 v[130:133], v[114:117], v[94:97], v[130:133]
	s_waitcnt lgkmcnt(11)
	v_mfma_f32_16x16x32_bf16 v[134:137], v[118:121], v[94:97], v[134:137]
	s_waitcnt lgkmcnt(10)
	v_mfma_f32_16x16x32_bf16 v[42:45], v[122:125], v[94:97], v[42:45]
	v_mfma_f32_16x16x32_bf16 v[58:61], v[110:113], v[98:101], v[58:61]
	ds_write_b128 v24, v[142:145] offset:61440
	s_waitcnt vmcnt(6)
	ds_write_b128 v25, v[178:181] offset:61440
	v_mfma_f32_16x16x32_bf16 v[62:65], v[114:117], v[98:101], v[62:65]
	v_mfma_f32_16x16x32_bf16 v[74:77], v[118:121], v[98:101], v[74:77]
	v_mfma_f32_16x16x32_bf16 v[46:49], v[122:125], v[98:101], v[46:49]
	v_mfma_f32_16x16x32_bf16 v[66:69], v[110:113], v[102:105], v[66:69]
	ds_write_b128 v26, v[152:155] offset:61440
	v_mfma_f32_16x16x32_bf16 v[78:81], v[114:117], v[102:105], v[78:81]
	v_mfma_f32_16x16x32_bf16 v[82:85], v[118:121], v[102:105], v[82:85]
	v_mfma_f32_16x16x32_bf16 v[50:53], v[122:125], v[102:105], v[50:53]
	v_mfma_f32_16x16x32_bf16 v[70:73], v[110:113], v[106:109], v[70:73]
	ds_write_b128 v27, v[156:159] offset:61440
	v_mfma_f32_16x16x32_bf16 v[86:89], v[114:117], v[106:109], v[86:89]
	v_mfma_f32_16x16x32_bf16 v[90:93], v[118:121], v[106:109], v[90:93]
	v_mfma_f32_16x16x32_bf16 v[54:57], v[122:125], v[106:109], v[54:57]
	s_waitcnt lgkmcnt(0)
	s_barrier
	ds_read_b128 v[94:97], v39 offset:61440
	ds_read_b128 v[98:101], v39 offset:64000
	ds_read_b128 v[102:105], v32 offset:5120
	ds_read_b128 v[106:109], v32 offset:7680
	ds_read_b128 v[110:113], v33
	ds_read_b128 v[114:117], v33 offset:2560
	ds_read_b128 v[118:121], v33 offset:5120
	ds_read_b128 v[122:125], v33 offset:7680
	v_mfma_f32_16x16x32_bf16 v[126:129], v[222:225], v[206:209], v[126:129]
	v_mfma_f32_16x16x32_bf16 v[130:133], v[226:229], v[206:209], v[130:133]
	v_mfma_f32_16x16x32_bf16 v[134:137], v[230:233], v[206:209], v[134:137]
	v_mfma_f32_16x16x32_bf16 v[42:45], v[234:237], v[206:209], v[42:45]
	v_mfma_f32_16x16x32_bf16 v[58:61], v[222:225], v[210:213], v[58:61]
	v_mfma_f32_16x16x32_bf16 v[62:65], v[226:229], v[210:213], v[62:65]
	v_mfma_f32_16x16x32_bf16 v[74:77], v[230:233], v[210:213], v[74:77]
	v_mfma_f32_16x16x32_bf16 v[46:49], v[234:237], v[210:213], v[46:49]
	v_mfma_f32_16x16x32_bf16 v[66:69], v[222:225], v[214:217], v[66:69]
	v_mfma_f32_16x16x32_bf16 v[78:81], v[226:229], v[214:217], v[78:81]
	v_mfma_f32_16x16x32_bf16 v[82:85], v[230:233], v[214:217], v[82:85]
	v_mfma_f32_16x16x32_bf16 v[50:53], v[234:237], v[214:217], v[50:53]
	v_mfma_f32_16x16x32_bf16 v[70:73], v[222:225], v[218:221], v[70:73]
	v_mfma_f32_16x16x32_bf16 v[86:89], v[226:229], v[218:221], v[86:89]
	v_mfma_f32_16x16x32_bf16 v[90:93], v[230:233], v[218:221], v[90:93]
	v_mfma_f32_16x16x32_bf16 v[54:57], v[234:237], v[218:221], v[54:57]
	global_load_dwordx4 v[138:141], v[2:3], off offset:1152
	global_load_dwordx4 v[142:145], v[8:9], off offset:1152
	global_load_dwordx4 v[152:155], v[10:11], off offset:1152
	global_load_dwordx4 v[156:159], v[12:13], off offset:1152
	global_load_dwordx4 v[174:177], v[14:15], off offset:1152
	global_load_dwordx4 v[178:181], v[16:17], off offset:1152
	ds_read_b128 v[206:209], v30 offset:61504
	ds_read_b128 v[210:213], v30 offset:64064
	ds_read_b128 v[214:217], v34 offset:64
	ds_read_b128 v[218:221], v35 offset:64
	ds_read_b128 v[222:225], v41 offset:64
	ds_read_b128 v[226:229], v36 offset:64
	ds_read_b128 v[230:233], v37 offset:64
	ds_read_b128 v[234:237], v38 offset:64
	s_waitcnt lgkmcnt(11)
;     ...
;   for (int k0 = 0; k0 < K; k0 += 128) {
;     G_READ(fa1, fb1, 0, 32);
;     if (k0 + 128 < K) G_LOAD(ra0, rb0, k0 + 128);
;     __builtin_amdgcn_sched_barrier(0);
;     G_MFMA_ST(fa0, fb0, ra1, rb1, 1);
;     __syncthreads();
;     G_READ(fa0, fb0, 1, 0);
;     __builtin_amdgcn_sched_barrier(0);
;     G_MFMA(fa1, fb1);
;     __builtin_amdgcn_sched_barrier(0);
;     G_READ(fa1, fb1, 1, 32);
;     if (k0 + 192 < K) G_LOAD(ra1, rb1, k0 + 192);
;     __builtin_amdgcn_sched_barrier(0);
;     if (k0 + 128 < K) {
;       G_MFMA_ST(fa0, fb0, ra0, rb0, 0);
;       __syncthreads();
;       G_READ(fa0, fb0, 0, 0);
;     } else {
;       G_MFMA(fa0, fb0);
;     }
;     __builtin_amdgcn_sched_barrier(0);
;     G_MFMA(fa1, fb1);
;     __builtin_amdgcn_sched_barrier(0);
;   }
	v_mfma_f32_16x16x32_bf16 v[126:129], v[110:113], v[94:97], v[126:129]
	s_waitcnt vmcnt(11)
	ds_write_b128 v22, v[182:185]
	s_waitcnt vmcnt(7)
	ds_write_b128 v23, v[198:201]
	s_waitcnt lgkmcnt(12)
	v_mfma_f32_16x16x32_bf16 v[130:133], v[114:117], v[94:97], v[130:133]
	s_waitcnt lgkmcnt(11)
	v_mfma_f32_16x16x32_bf16 v[134:137], v[118:121], v[94:97], v[134:137]
	s_waitcnt lgkmcnt(10)
	v_mfma_f32_16x16x32_bf16 v[42:45], v[122:125], v[94:97], v[42:45]
	v_mfma_f32_16x16x32_bf16 v[58:61], v[110:113], v[98:101], v[58:61]
	ds_write_b128 v22, v[186:189] offset:10240
	s_waitcnt vmcnt(6)
	ds_write_b128 v25, v[202:205]
	v_mfma_f32_16x16x32_bf16 v[62:65], v[114:117], v[98:101], v[62:65]
	v_mfma_f32_16x16x32_bf16 v[74:77], v[118:121], v[98:101], v[74:77]
	v_mfma_f32_16x16x32_bf16 v[46:49], v[122:125], v[98:101], v[46:49]
	v_mfma_f32_16x16x32_bf16 v[66:69], v[110:113], v[102:105], v[66:69]
	ds_write_b128 v22, v[190:193] offset:20480
	v_mfma_f32_16x16x32_bf16 v[78:81], v[114:117], v[102:105], v[78:81]
	v_mfma_f32_16x16x32_bf16 v[82:85], v[118:121], v[102:105], v[82:85]
	v_mfma_f32_16x16x32_bf16 v[50:53], v[122:125], v[102:105], v[50:53]
	v_mfma_f32_16x16x32_bf16 v[70:73], v[110:113], v[106:109], v[70:73]
	ds_write_b128 v22, v[194:197] offset:30720
	v_mfma_f32_16x16x32_bf16 v[86:89], v[114:117], v[106:109], v[86:89]
	v_mfma_f32_16x16x32_bf16 v[90:93], v[118:121], v[106:109], v[90:93]
	v_mfma_f32_16x16x32_bf16 v[54:57], v[122:125], v[106:109], v[54:57]
	s_waitcnt lgkmcnt(0)
	s_barrier
	ds_read_b128 v[94:97], v39
	ds_read_b128 v[98:101], v39 offset:2560
	ds_read_b128 v[102:105], v39 offset:5120
	ds_read_b128 v[106:109], v39 offset:7680
	ds_read_b128 v[110:113], v40 offset:40960
	ds_read_b128 v[114:117], v40 offset:43520
	ds_read_b128 v[118:121], v40 offset:46080
	ds_read_b128 v[122:125], v40 offset:48640
	v_mfma_f32_16x16x32_bf16 v[126:129], v[222:225], v[206:209], v[126:129]
	v_mfma_f32_16x16x32_bf16 v[130:133], v[226:229], v[206:209], v[130:133]
	v_mfma_f32_16x16x32_bf16 v[134:137], v[230:233], v[206:209], v[134:137]
	v_mfma_f32_16x16x32_bf16 v[42:45], v[234:237], v[206:209], v[42:45]
	v_mfma_f32_16x16x32_bf16 v[58:61], v[222:225], v[210:213], v[58:61]
	v_mfma_f32_16x16x32_bf16 v[62:65], v[226:229], v[210:213], v[62:65]
	v_mfma_f32_16x16x32_bf16 v[74:77], v[230:233], v[210:213], v[74:77]
	v_mfma_f32_16x16x32_bf16 v[46:49], v[234:237], v[210:213], v[46:49]
	v_mfma_f32_16x16x32_bf16 v[66:69], v[222:225], v[214:217], v[66:69]
	v_mfma_f32_16x16x32_bf16 v[78:81], v[226:229], v[214:217], v[78:81]
	v_mfma_f32_16x16x32_bf16 v[82:85], v[230:233], v[214:217], v[82:85]
	v_mfma_f32_16x16x32_bf16 v[50:53], v[234:237], v[214:217], v[50:53]
	v_mfma_f32_16x16x32_bf16 v[70:73], v[222:225], v[218:221], v[70:73]
	v_mfma_f32_16x16x32_bf16 v[86:89], v[226:229], v[218:221], v[86:89]
	v_mfma_f32_16x16x32_bf16 v[90:93], v[230:233], v[218:221], v[90:93]
	v_mfma_f32_16x16x32_bf16 v[54:57], v[234:237], v[218:221], v[54:57]
	global_load_dwordx4 v[182:185], v[2:3], off offset:1280
	global_load_dwordx4 v[186:189], v[8:9], off offset:1280
	global_load_dwordx4 v[190:193], v[10:11], off offset:1280
	global_load_dwordx4 v[194:197], v[12:13], off offset:1280
	global_load_dwordx4 v[198:201], v[14:15], off offset:1280
	global_load_dwordx4 v[202:205], v[16:17], off offset:1280
	ds_read_b128 v[206:209], v30 offset:64
	ds_read_b128 v[210:213], v30 offset:2624
	ds_read_b128 v[214:217], v30 offset:5184
	ds_read_b128 v[218:221], v30 offset:7744
	ds_read_b128 v[222:225], v31 offset:41024
	ds_read_b128 v[226:229], v31 offset:43584
	ds_read_b128 v[230:233], v31 offset:46144
	ds_read_b128 v[234:237], v31 offset:48704
	s_waitcnt lgkmcnt(11)
	v_mfma_f32_16x16x32_bf16 v[126:129], v[110:113], v[94:97], v[126:129]
	s_waitcnt vmcnt(11)
	ds_write_b128 v22, v[138:141] offset:61440
	s_waitcnt vmcnt(7)
	ds_write_b128 v23, v[174:177] offset:61440
	s_waitcnt lgkmcnt(12)
	v_mfma_f32_16x16x32_bf16 v[130:133], v[114:117], v[94:97], v[130:133]
	s_waitcnt lgkmcnt(11)
	v_mfma_f32_16x16x32_bf16 v[134:137], v[118:121], v[94:97], v[134:137]
	s_waitcnt lgkmcnt(10)
	v_mfma_f32_16x16x32_bf16 v[42:45], v[122:125], v[94:97], v[42:45]
	v_mfma_f32_16x16x32_bf16 v[58:61], v[110:113], v[98:101], v[58:61]
	ds_write_b128 v24, v[142:145] offset:61440
	s_waitcnt vmcnt(6)
	ds_write_b128 v25, v[178:181] offset:61440
	v_mfma_f32_16x16x32_bf16 v[62:65], v[114:117], v[98:101], v[62:65]
	v_mfma_f32_16x16x32_bf16 v[74:77], v[118:121], v[98:101], v[74:77]
	v_mfma_f32_16x16x32_bf16 v[46:49], v[122:125], v[98:101], v[46:49]
	v_mfma_f32_16x16x32_bf16 v[66:69], v[110:113], v[102:105], v[66:69]
	ds_write_b128 v26, v[152:155] offset:61440
	v_mfma_f32_16x16x32_bf16 v[78:81], v[114:117], v[102:105], v[78:81]
	v_mfma_f32_16x16x32_bf16 v[82:85], v[118:121], v[102:105], v[82:85]
	v_mfma_f32_16x16x32_bf16 v[50:53], v[122:125], v[102:105], v[50:53]
	v_mfma_f32_16x16x32_bf16 v[70:73], v[110:113], v[106:109], v[70:73]
	ds_write_b128 v27, v[156:159] offset:61440
	v_mfma_f32_16x16x32_bf16 v[86:89], v[114:117], v[106:109], v[86:89]
	v_mfma_f32_16x16x32_bf16 v[90:93], v[118:121], v[106:109], v[90:93]
	v_mfma_f32_16x16x32_bf16 v[54:57], v[122:125], v[106:109], v[54:57]
	s_waitcnt lgkmcnt(0)
	s_barrier
;     ...
;   for (int k0 = 0; k0 < K; k0 += 128) {
;     G_READ(fa1, fb1, 0, 32);
;     if (k0 + 128 < K) G_LOAD(ra0, rb0, k0 + 128);
;     __builtin_amdgcn_sched_barrier(0);
;     G_MFMA_ST(fa0, fb0, ra1, rb1, 1);
;     __syncthreads();
;     G_READ(fa0, fb0, 1, 0);
;     __builtin_amdgcn_sched_barrier(0);
;     G_MFMA(fa1, fb1);
;     __builtin_amdgcn_sched_barrier(0);
;     G_READ(fa1, fb1, 1, 32);
;     if (k0 + 192 < K) G_LOAD(ra1, rb1, k0 + 192);
;     __builtin_amdgcn_sched_barrier(0);
;     if (k0 + 128 < K) {
;       G_MFMA_ST(fa0, fb0, ra0, rb0, 0);
;       __syncthreads();
;       G_READ(fa0, fb0, 0, 0);
;     } else {
;       G_MFMA(fa0, fb0);
;     }
;     __builtin_amdgcn_sched_barrier(0);
;     G_MFMA(fa1, fb1);
;     __builtin_amdgcn_sched_barrier(0);
;   }
	ds_read_b128 v[94:97], v39 offset:61440
	ds_read_b128 v[98:101], v39 offset:64000
	ds_read_b128 v[102:105], v32 offset:5120
	ds_read_b128 v[106:109], v32 offset:7680
	ds_read_b128 v[110:113], v33
	ds_read_b128 v[114:117], v33 offset:2560
	ds_read_b128 v[118:121], v33 offset:5120
	ds_read_b128 v[122:125], v33 offset:7680
	v_mfma_f32_16x16x32_bf16 v[126:129], v[222:225], v[206:209], v[126:129]
	v_mfma_f32_16x16x32_bf16 v[130:133], v[226:229], v[206:209], v[130:133]
	v_mfma_f32_16x16x32_bf16 v[134:137], v[230:233], v[206:209], v[134:137]
	v_mfma_f32_16x16x32_bf16 v[42:45], v[234:237], v[206:209], v[42:45]
	v_mfma_f32_16x16x32_bf16 v[58:61], v[222:225], v[210:213], v[58:61]
	v_mfma_f32_16x16x32_bf16 v[62:65], v[226:229], v[210:213], v[62:65]
	v_mfma_f32_16x16x32_bf16 v[74:77], v[230:233], v[210:213], v[74:77]
	v_mfma_f32_16x16x32_bf16 v[46:49], v[234:237], v[210:213], v[46:49]
	v_mfma_f32_16x16x32_bf16 v[66:69], v[222:225], v[214:217], v[66:69]
	v_mfma_f32_16x16x32_bf16 v[78:81], v[226:229], v[214:217], v[78:81]
	v_mfma_f32_16x16x32_bf16 v[82:85], v[230:233], v[214:217], v[82:85]
	v_mfma_f32_16x16x32_bf16 v[50:53], v[234:237], v[214:217], v[50:53]
	v_mfma_f32_16x16x32_bf16 v[70:73], v[222:225], v[218:221], v[70:73]
	v_mfma_f32_16x16x32_bf16 v[86:89], v[226:229], v[218:221], v[86:89]
	v_mfma_f32_16x16x32_bf16 v[90:93], v[230:233], v[218:221], v[90:93]
	v_mfma_f32_16x16x32_bf16 v[54:57], v[234:237], v[218:221], v[54:57]
	global_load_dwordx4 v[138:141], v[2:3], off offset:1408
	global_load_dwordx4 v[142:145], v[8:9], off offset:1408
	global_load_dwordx4 v[152:155], v[10:11], off offset:1408
	global_load_dwordx4 v[156:159], v[12:13], off offset:1408
	global_load_dwordx4 v[174:177], v[14:15], off offset:1408
	global_load_dwordx4 v[178:181], v[16:17], off offset:1408
	ds_read_b128 v[206:209], v30 offset:61504
	ds_read_b128 v[210:213], v30 offset:64064
	ds_read_b128 v[214:217], v34 offset:64
	ds_read_b128 v[218:221], v35 offset:64
	ds_read_b128 v[222:225], v41 offset:64
	ds_read_b128 v[226:229], v36 offset:64
	ds_read_b128 v[230:233], v37 offset:64
	ds_read_b128 v[234:237], v38 offset:64
	s_waitcnt lgkmcnt(11)
	v_mfma_f32_16x16x32_bf16 v[126:129], v[110:113], v[94:97], v[126:129]
	s_waitcnt vmcnt(11)
	ds_write_b128 v22, v[182:185]
	s_waitcnt vmcnt(7)
	ds_write_b128 v23, v[198:201]
	s_waitcnt lgkmcnt(12)
	v_mfma_f32_16x16x32_bf16 v[130:133], v[114:117], v[94:97], v[130:133]
	s_waitcnt lgkmcnt(11)
	v_mfma_f32_16x16x32_bf16 v[134:137], v[118:121], v[94:97], v[134:137]
	s_waitcnt lgkmcnt(10)
	v_mfma_f32_16x16x32_bf16 v[42:45], v[122:125], v[94:97], v[42:45]
	v_mfma_f32_16x16x32_bf16 v[58:61], v[110:113], v[98:101], v[58:61]
	ds_write_b128 v22, v[186:189] offset:10240
	s_waitcnt vmcnt(6)
	ds_write_b128 v25, v[202:205]
	v_mfma_f32_16x16x32_bf16 v[62:65], v[114:117], v[98:101], v[62:65]
	v_mfma_f32_16x16x32_bf16 v[74:77], v[118:121], v[98:101], v[74:77]
	v_mfma_f32_16x16x32_bf16 v[46:49], v[122:125], v[98:101], v[46:49]
	v_mfma_f32_16x16x32_bf16 v[66:69], v[110:113], v[102:105], v[66:69]
	ds_write_b128 v22, v[190:193] offset:20480
	v_mfma_f32_16x16x32_bf16 v[78:81], v[114:117], v[102:105], v[78:81]
	v_mfma_f32_16x16x32_bf16 v[82:85], v[118:121], v[102:105], v[82:85]
	v_mfma_f32_16x16x32_bf16 v[50:53], v[122:125], v[102:105], v[50:53]
	v_mfma_f32_16x16x32_bf16 v[70:73], v[110:113], v[106:109], v[70:73]
	ds_write_b128 v22, v[194:197] offset:30720
	v_mfma_f32_16x16x32_bf16 v[86:89], v[114:117], v[106:109], v[86:89]
	v_mfma_f32_16x16x32_bf16 v[90:93], v[118:121], v[106:109], v[90:93]
	v_mfma_f32_16x16x32_bf16 v[54:57], v[122:125], v[106:109], v[54:57]
	s_waitcnt lgkmcnt(0)
	s_barrier
	ds_read_b128 v[94:97], v39
	ds_read_b128 v[98:101], v39 offset:2560
	ds_read_b128 v[102:105], v39 offset:5120
	ds_read_b128 v[106:109], v39 offset:7680
	ds_read_b128 v[110:113], v40 offset:40960
	ds_read_b128 v[114:117], v40 offset:43520
	ds_read_b128 v[118:121], v40 offset:46080
	ds_read_b128 v[122:125], v40 offset:48640
	v_mfma_f32_16x16x32_bf16 v[126:129], v[222:225], v[206:209], v[126:129]
	v_mfma_f32_16x16x32_bf16 v[130:133], v[226:229], v[206:209], v[130:133]
	v_mfma_f32_16x16x32_bf16 v[134:137], v[230:233], v[206:209], v[134:137]
	v_mfma_f32_16x16x32_bf16 v[42:45], v[234:237], v[206:209], v[42:45]
	v_mfma_f32_16x16x32_bf16 v[58:61], v[222:225], v[210:213], v[58:61]
	v_mfma_f32_16x16x32_bf16 v[62:65], v[226:229], v[210:213], v[62:65]
	v_mfma_f32_16x16x32_bf16 v[74:77], v[230:233], v[210:213], v[74:77]
	v_mfma_f32_16x16x32_bf16 v[46:49], v[234:237], v[210:213], v[46:49]
	v_mfma_f32_16x16x32_bf16 v[66:69], v[222:225], v[214:217], v[66:69]
	v_mfma_f32_16x16x32_bf16 v[78:81], v[226:229], v[214:217], v[78:81]
	v_mfma_f32_16x16x32_bf16 v[82:85], v[230:233], v[214:217], v[82:85]
	v_mfma_f32_16x16x32_bf16 v[50:53], v[234:237], v[214:217], v[50:53]
	v_mfma_f32_16x16x32_bf16 v[70:73], v[222:225], v[218:221], v[70:73]
	v_mfma_f32_16x16x32_bf16 v[86:89], v[226:229], v[218:221], v[86:89]
	v_mfma_f32_16x16x32_bf16 v[90:93], v[230:233], v[218:221], v[90:93]
	v_mfma_f32_16x16x32_bf16 v[54:57], v[234:237], v[218:221], v[54:57]
	global_load_dwordx4 v[182:185], v[2:3], off offset:1536
	global_load_dwordx4 v[186:189], v[8:9], off offset:1536
	global_load_dwordx4 v[190:193], v[10:11], off offset:1536
	global_load_dwordx4 v[194:197], v[12:13], off offset:1536
	global_load_dwordx4 v[198:201], v[14:15], off offset:1536
	global_load_dwordx4 v[202:205], v[16:17], off offset:1536
	ds_read_b128 v[206:209], v30 offset:64
	ds_read_b128 v[210:213], v30 offset:2624
	ds_read_b128 v[214:217], v30 offset:5184
	ds_read_b128 v[218:221], v30 offset:7744
	ds_read_b128 v[222:225], v31 offset:41024
	ds_read_b128 v[226:229], v31 offset:43584
	ds_read_b128 v[230:233], v31 offset:46144
	ds_read_b128 v[234:237], v31 offset:48704
	s_waitcnt lgkmcnt(11)
;     ...
;   for (int k0 = 0; k0 < K; k0 += 128) {
;     G_READ(fa1, fb1, 0, 32);
;     if (k0 + 128 < K) G_LOAD(ra0, rb0, k0 + 128);
;     __builtin_amdgcn_sched_barrier(0);
;     G_MFMA_ST(fa0, fb0, ra1, rb1, 1);
;     __syncthreads();
;     G_READ(fa0, fb0, 1, 0);
;     __builtin_amdgcn_sched_barrier(0);
;     G_MFMA(fa1, fb1);
;     __builtin_amdgcn_sched_barrier(0);
;     G_READ(fa1, fb1, 1, 32);
;     if (k0 + 192 < K) G_LOAD(ra1, rb1, k0 + 192);
;     __builtin_amdgcn_sched_barrier(0);
;     if (k0 + 128 < K) {
;       G_MFMA_ST(fa0, fb0, ra0, rb0, 0);
;       __syncthreads();
;       G_READ(fa0, fb0, 0, 0);
;     } else {
;       G_MFMA(fa0, fb0);
;     }
;     __builtin_amdgcn_sched_barrier(0);
;     G_MFMA(fa1, fb1);
;     __builtin_amdgcn_sched_barrier(0);
;   }
	v_mfma_f32_16x16x32_bf16 v[126:129], v[110:113], v[94:97], v[126:129]
	s_waitcnt vmcnt(11)
	ds_write_b128 v22, v[138:141] offset:61440
	s_waitcnt vmcnt(7)
	ds_write_b128 v23, v[174:177] offset:61440
	s_waitcnt lgkmcnt(12)
	v_mfma_f32_16x16x32_bf16 v[130:133], v[114:117], v[94:97], v[130:133]
	s_waitcnt lgkmcnt(11)
	v_mfma_f32_16x16x32_bf16 v[134:137], v[118:121], v[94:97], v[134:137]
	s_waitcnt lgkmcnt(10)
	v_mfma_f32_16x16x32_bf16 v[42:45], v[122:125], v[94:97], v[42:45]
	v_mfma_f32_16x16x32_bf16 v[58:61], v[110:113], v[98:101], v[58:61]
	ds_write_b128 v24, v[142:145] offset:61440
	s_waitcnt vmcnt(6)
	ds_write_b128 v25, v[178:181] offset:61440
	v_mfma_f32_16x16x32_bf16 v[62:65], v[114:117], v[98:101], v[62:65]
	v_mfma_f32_16x16x32_bf16 v[74:77], v[118:121], v[98:101], v[74:77]
	v_mfma_f32_16x16x32_bf16 v[46:49], v[122:125], v[98:101], v[46:49]
	v_mfma_f32_16x16x32_bf16 v[66:69], v[110:113], v[102:105], v[66:69]
	ds_write_b128 v26, v[152:155] offset:61440
	v_mfma_f32_16x16x32_bf16 v[78:81], v[114:117], v[102:105], v[78:81]
	v_mfma_f32_16x16x32_bf16 v[82:85], v[118:121], v[102:105], v[82:85]
	v_mfma_f32_16x16x32_bf16 v[50:53], v[122:125], v[102:105], v[50:53]
	v_mfma_f32_16x16x32_bf16 v[70:73], v[110:113], v[106:109], v[70:73]
	ds_write_b128 v27, v[156:159] offset:61440
	v_mfma_f32_16x16x32_bf16 v[86:89], v[114:117], v[106:109], v[86:89]
	v_mfma_f32_16x16x32_bf16 v[90:93], v[118:121], v[106:109], v[90:93]
	v_mfma_f32_16x16x32_bf16 v[54:57], v[122:125], v[106:109], v[54:57]
	s_waitcnt lgkmcnt(0)
	s_barrier
	ds_read_b128 v[94:97], v39 offset:61440
	ds_read_b128 v[98:101], v39 offset:64000
	ds_read_b128 v[102:105], v32 offset:5120
	ds_read_b128 v[106:109], v32 offset:7680
	ds_read_b128 v[110:113], v33
	ds_read_b128 v[114:117], v33 offset:2560
	ds_read_b128 v[118:121], v33 offset:5120
	ds_read_b128 v[122:125], v33 offset:7680
	v_mfma_f32_16x16x32_bf16 v[126:129], v[222:225], v[206:209], v[126:129]
	v_mfma_f32_16x16x32_bf16 v[130:133], v[226:229], v[206:209], v[130:133]
	v_mfma_f32_16x16x32_bf16 v[134:137], v[230:233], v[206:209], v[134:137]
	v_mfma_f32_16x16x32_bf16 v[42:45], v[234:237], v[206:209], v[42:45]
	v_mfma_f32_16x16x32_bf16 v[58:61], v[222:225], v[210:213], v[58:61]
	v_mfma_f32_16x16x32_bf16 v[62:65], v[226:229], v[210:213], v[62:65]
	v_mfma_f32_16x16x32_bf16 v[74:77], v[230:233], v[210:213], v[74:77]
	v_mfma_f32_16x16x32_bf16 v[46:49], v[234:237], v[210:213], v[46:49]
	v_mfma_f32_16x16x32_bf16 v[66:69], v[222:225], v[214:217], v[66:69]
	v_mfma_f32_16x16x32_bf16 v[78:81], v[226:229], v[214:217], v[78:81]
	v_mfma_f32_16x16x32_bf16 v[82:85], v[230:233], v[214:217], v[82:85]
	v_mfma_f32_16x16x32_bf16 v[50:53], v[234:237], v[214:217], v[50:53]
	v_mfma_f32_16x16x32_bf16 v[70:73], v[222:225], v[218:221], v[70:73]
	v_mfma_f32_16x16x32_bf16 v[86:89], v[226:229], v[218:221], v[86:89]
	v_mfma_f32_16x16x32_bf16 v[90:93], v[230:233], v[218:221], v[90:93]
	v_mfma_f32_16x16x32_bf16 v[54:57], v[234:237], v[218:221], v[54:57]
	global_load_dwordx4 v[138:141], v[2:3], off offset:1664
	global_load_dwordx4 v[142:145], v[8:9], off offset:1664
	global_load_dwordx4 v[152:155], v[10:11], off offset:1664
	global_load_dwordx4 v[156:159], v[12:13], off offset:1664
	global_load_dwordx4 v[174:177], v[14:15], off offset:1664
	global_load_dwordx4 v[178:181], v[16:17], off offset:1664
	ds_read_b128 v[206:209], v30 offset:61504
	ds_read_b128 v[210:213], v30 offset:64064
	ds_read_b128 v[214:217], v34 offset:64
	ds_read_b128 v[218:221], v35 offset:64
	ds_read_b128 v[222:225], v41 offset:64
	ds_read_b128 v[226:229], v36 offset:64
	ds_read_b128 v[230:233], v37 offset:64
	ds_read_b128 v[234:237], v38 offset:64
	s_waitcnt lgkmcnt(11)
	v_mfma_f32_16x16x32_bf16 v[126:129], v[110:113], v[94:97], v[126:129]
	s_waitcnt vmcnt(11)
	ds_write_b128 v22, v[182:185]
	s_waitcnt vmcnt(7)
	ds_write_b128 v23, v[198:201]
	s_waitcnt lgkmcnt(12)
	v_mfma_f32_16x16x32_bf16 v[130:133], v[114:117], v[94:97], v[130:133]
	s_waitcnt lgkmcnt(11)
	v_mfma_f32_16x16x32_bf16 v[134:137], v[118:121], v[94:97], v[134:137]
	s_waitcnt lgkmcnt(10)
	v_mfma_f32_16x16x32_bf16 v[42:45], v[122:125], v[94:97], v[42:45]
	v_mfma_f32_16x16x32_bf16 v[58:61], v[110:113], v[98:101], v[58:61]
	ds_write_b128 v22, v[186:189] offset:10240
	s_waitcnt vmcnt(6)
	ds_write_b128 v25, v[202:205]
	v_mfma_f32_16x16x32_bf16 v[62:65], v[114:117], v[98:101], v[62:65]
	v_mfma_f32_16x16x32_bf16 v[74:77], v[118:121], v[98:101], v[74:77]
	v_mfma_f32_16x16x32_bf16 v[46:49], v[122:125], v[98:101], v[46:49]
	v_mfma_f32_16x16x32_bf16 v[66:69], v[110:113], v[102:105], v[66:69]
	ds_write_b128 v22, v[190:193] offset:20480
	v_mfma_f32_16x16x32_bf16 v[78:81], v[114:117], v[102:105], v[78:81]
	v_mfma_f32_16x16x32_bf16 v[82:85], v[118:121], v[102:105], v[82:85]
	v_mfma_f32_16x16x32_bf16 v[50:53], v[122:125], v[102:105], v[50:53]
	v_mfma_f32_16x16x32_bf16 v[70:73], v[110:113], v[106:109], v[70:73]
	ds_write_b128 v22, v[194:197] offset:30720
	v_mfma_f32_16x16x32_bf16 v[86:89], v[114:117], v[106:109], v[86:89]
	v_mfma_f32_16x16x32_bf16 v[90:93], v[118:121], v[106:109], v[90:93]
	v_mfma_f32_16x16x32_bf16 v[54:57], v[122:125], v[106:109], v[54:57]
	s_waitcnt lgkmcnt(0)
	s_barrier
;     ...
;   for (int k0 = 0; k0 < K; k0 += 128) {
;     G_READ(fa1, fb1, 0, 32);
;     if (k0 + 128 < K) G_LOAD(ra0, rb0, k0 + 128);
;     __builtin_amdgcn_sched_barrier(0);
;     G_MFMA_ST(fa0, fb0, ra1, rb1, 1);
;     __syncthreads();
;     G_READ(fa0, fb0, 1, 0);
;     __builtin_amdgcn_sched_barrier(0);
;     G_MFMA(fa1, fb1);
;     __builtin_amdgcn_sched_barrier(0);
;     G_READ(fa1, fb1, 1, 32);
;     if (k0 + 192 < K) G_LOAD(ra1, rb1, k0 + 192);
;     __builtin_amdgcn_sched_barrier(0);
;     if (k0 + 128 < K) {
;       G_MFMA_ST(fa0, fb0, ra0, rb0, 0);
;       __syncthreads();
;       G_READ(fa0, fb0, 0, 0);
;     } else {
;       G_MFMA(fa0, fb0);
;     }
;     __builtin_amdgcn_sched_barrier(0);
;     G_MFMA(fa1, fb1);
;     __builtin_amdgcn_sched_barrier(0);
;   }
	ds_read_b128 v[94:97], v39
	ds_read_b128 v[98:101], v39 offset:2560
	ds_read_b128 v[102:105], v39 offset:5120
	ds_read_b128 v[106:109], v39 offset:7680
	ds_read_b128 v[110:113], v40 offset:40960
	ds_read_b128 v[114:117], v40 offset:43520
	ds_read_b128 v[118:121], v40 offset:46080
	ds_read_b128 v[122:125], v40 offset:48640
	v_mfma_f32_16x16x32_bf16 v[126:129], v[222:225], v[206:209], v[126:129]
	v_mfma_f32_16x16x32_bf16 v[130:133], v[226:229], v[206:209], v[130:133]
	v_mfma_f32_16x16x32_bf16 v[134:137], v[230:233], v[206:209], v[134:137]
	v_mfma_f32_16x16x32_bf16 v[42:45], v[234:237], v[206:209], v[42:45]
	v_mfma_f32_16x16x32_bf16 v[58:61], v[222:225], v[210:213], v[58:61]
	v_mfma_f32_16x16x32_bf16 v[62:65], v[226:229], v[210:213], v[62:65]
	v_mfma_f32_16x16x32_bf16 v[74:77], v[230:233], v[210:213], v[74:77]
	v_mfma_f32_16x16x32_bf16 v[46:49], v[234:237], v[210:213], v[46:49]
	v_mfma_f32_16x16x32_bf16 v[66:69], v[222:225], v[214:217], v[66:69]
	v_mfma_f32_16x16x32_bf16 v[78:81], v[226:229], v[214:217], v[78:81]
	v_mfma_f32_16x16x32_bf16 v[82:85], v[230:233], v[214:217], v[82:85]
	v_mfma_f32_16x16x32_bf16 v[50:53], v[234:237], v[214:217], v[50:53]
	v_mfma_f32_16x16x32_bf16 v[70:73], v[222:225], v[218:221], v[70:73]
	v_mfma_f32_16x16x32_bf16 v[86:89], v[226:229], v[218:221], v[86:89]
	v_mfma_f32_16x16x32_bf16 v[90:93], v[230:233], v[218:221], v[90:93]
	v_mfma_f32_16x16x32_bf16 v[54:57], v[234:237], v[218:221], v[54:57]
	global_load_dwordx4 v[182:185], v[2:3], off offset:1792
	global_load_dwordx4 v[186:189], v[8:9], off offset:1792
	global_load_dwordx4 v[190:193], v[10:11], off offset:1792
	global_load_dwordx4 v[194:197], v[12:13], off offset:1792
	global_load_dwordx4 v[198:201], v[14:15], off offset:1792
	global_load_dwordx4 v[202:205], v[16:17], off offset:1792
	ds_read_b128 v[206:209], v30 offset:64
	ds_read_b128 v[210:213], v30 offset:2624
	ds_read_b128 v[214:217], v30 offset:5184
	ds_read_b128 v[218:221], v30 offset:7744
	ds_read_b128 v[222:225], v31 offset:41024
	ds_read_b128 v[226:229], v31 offset:43584
	ds_read_b128 v[230:233], v31 offset:46144
	ds_read_b128 v[234:237], v31 offset:48704
	s_waitcnt lgkmcnt(11)
	v_mfma_f32_16x16x32_bf16 v[126:129], v[110:113], v[94:97], v[126:129]
	s_waitcnt vmcnt(11)
	ds_write_b128 v22, v[138:141] offset:61440
	s_waitcnt vmcnt(7)
	ds_write_b128 v23, v[174:177] offset:61440
	s_waitcnt lgkmcnt(12)
	v_mfma_f32_16x16x32_bf16 v[130:133], v[114:117], v[94:97], v[130:133]
	s_waitcnt lgkmcnt(11)
	v_mfma_f32_16x16x32_bf16 v[134:137], v[118:121], v[94:97], v[134:137]
	s_waitcnt lgkmcnt(10)
	v_mfma_f32_16x16x32_bf16 v[42:45], v[122:125], v[94:97], v[42:45]
	v_mfma_f32_16x16x32_bf16 v[58:61], v[110:113], v[98:101], v[58:61]
	ds_write_b128 v24, v[142:145] offset:61440
	s_waitcnt vmcnt(6)
	ds_write_b128 v25, v[178:181] offset:61440
	v_mfma_f32_16x16x32_bf16 v[62:65], v[114:117], v[98:101], v[62:65]
	v_mfma_f32_16x16x32_bf16 v[74:77], v[118:121], v[98:101], v[74:77]
	v_mfma_f32_16x16x32_bf16 v[46:49], v[122:125], v[98:101], v[46:49]
	v_mfma_f32_16x16x32_bf16 v[66:69], v[110:113], v[102:105], v[66:69]
	ds_write_b128 v26, v[152:155] offset:61440
	v_mfma_f32_16x16x32_bf16 v[78:81], v[114:117], v[102:105], v[78:81]
	v_mfma_f32_16x16x32_bf16 v[82:85], v[118:121], v[102:105], v[82:85]
	v_mfma_f32_16x16x32_bf16 v[50:53], v[122:125], v[102:105], v[50:53]
	v_mfma_f32_16x16x32_bf16 v[70:73], v[110:113], v[106:109], v[70:73]
	ds_write_b128 v27, v[156:159] offset:61440
	v_mfma_f32_16x16x32_bf16 v[86:89], v[114:117], v[106:109], v[86:89]
	v_mfma_f32_16x16x32_bf16 v[90:93], v[118:121], v[106:109], v[90:93]
	v_mfma_f32_16x16x32_bf16 v[54:57], v[122:125], v[106:109], v[54:57]
	s_waitcnt lgkmcnt(0)
	s_barrier
;     ...
;   for (int k0 = 0; k0 < K; k0 += 128) {
;     G_READ(fa1, fb1, 0, 32);
;     if (k0 + 128 < K) G_LOAD(ra0, rb0, k0 + 128);
;     __builtin_amdgcn_sched_barrier(0);
;     G_MFMA_ST(fa0, fb0, ra1, rb1, 1);
;     __syncthreads();
;     G_READ(fa0, fb0, 1, 0);
;     __builtin_amdgcn_sched_barrier(0);
;     G_MFMA(fa1, fb1);
;     __builtin_amdgcn_sched_barrier(0);
;     G_READ(fa1, fb1, 1, 32);
;     if (k0 + 192 < K) G_LOAD(ra1, rb1, k0 + 192);
;     __builtin_amdgcn_sched_barrier(0);
;     if (k0 + 128 < K) {
;       G_MFMA_ST(fa0, fb0, ra0, rb0, 0);
;       __syncthreads();
;       G_READ(fa0, fb0, 0, 0);
;     } else {
;       G_MFMA(fa0, fb0);
;     }
;     __builtin_amdgcn_sched_barrier(0);
;     G_MFMA(fa1, fb1);
;     __builtin_amdgcn_sched_barrier(0);
;   }
; __device__ __forceinline__ void phase_inproj(const Params& p, const int tidx) {
;     ...
;   for (int tile = blockIdx.x, rnd = 0; tile < 128 * NTN; tile += gridDim.x, rnd++) {
;     int mt = tile / NTN, nt = tile % NTN;
;     if (swz) {
;       int j = rnd * 32 + li;
;       int g = j / (4 * NTN), rem = j % (4 * NTN);
;       nt = rem >> 2;
;       mt = xcd * 16 + g * 4 + (rem & 3);
;     }
	ds_read_b128 v[94:97], v39 offset:61440
	ds_read_b128 v[98:101], v39 offset:64000
	ds_read_b128 v[102:105], v32 offset:5120
	ds_read_b128 v[106:109], v32 offset:7680
	ds_read_b128 v[110:113], v33
	ds_read_b128 v[114:117], v33 offset:2560
	ds_read_b128 v[118:121], v33 offset:5120
	ds_read_b128 v[122:125], v33 offset:7680
	v_mfma_f32_16x16x32_bf16 v[126:129], v[222:225], v[206:209], v[126:129]
	v_mfma_f32_16x16x32_bf16 v[130:133], v[226:229], v[206:209], v[130:133]
	v_mfma_f32_16x16x32_bf16 v[134:137], v[230:233], v[206:209], v[134:137]
	v_mfma_f32_16x16x32_bf16 v[42:45], v[234:237], v[206:209], v[42:45]
	v_mfma_f32_16x16x32_bf16 v[58:61], v[222:225], v[210:213], v[58:61]
	v_mfma_f32_16x16x32_bf16 v[62:65], v[226:229], v[210:213], v[62:65]
	v_mfma_f32_16x16x32_bf16 v[74:77], v[230:233], v[210:213], v[74:77]
	v_mfma_f32_16x16x32_bf16 v[46:49], v[234:237], v[210:213], v[46:49]
	v_mfma_f32_16x16x32_bf16 v[66:69], v[222:225], v[214:217], v[66:69]
	v_mfma_f32_16x16x32_bf16 v[78:81], v[226:229], v[214:217], v[78:81]
	v_mfma_f32_16x16x32_bf16 v[82:85], v[230:233], v[214:217], v[82:85]
	v_mfma_f32_16x16x32_bf16 v[50:53], v[234:237], v[214:217], v[50:53]
	v_mfma_f32_16x16x32_bf16 v[70:73], v[222:225], v[218:221], v[70:73]
	v_mfma_f32_16x16x32_bf16 v[86:89], v[226:229], v[218:221], v[86:89]
	v_mfma_f32_16x16x32_bf16 v[90:93], v[230:233], v[218:221], v[90:93]
	v_mfma_f32_16x16x32_bf16 v[54:57], v[234:237], v[218:221], v[54:57]
	global_load_dwordx4 v[138:141], v[2:3], off offset:1920
	global_load_dwordx4 v[142:145], v[8:9], off offset:1920
	s_nop 0
	global_load_dwordx4 v[8:11], v[10:11], off offset:1920
	s_nop 0
	global_load_dwordx4 v[152:155], v[12:13], off offset:1920
	s_nop 0
	global_load_dwordx4 v[12:15], v[14:15], off offset:1920
	s_nop 0
	global_load_dwordx4 v[156:159], v[16:17], off offset:1920
	ds_read_b128 v[174:177], v30 offset:61504
	ds_read_b128 v[178:181], v30 offset:64064
	ds_read_b128 v[206:209], v34 offset:64
	ds_read_b128 v[210:213], v35 offset:64
	ds_read_b128 v[214:217], v41 offset:64
	ds_read_b128 v[218:221], v36 offset:64
	ds_read_b128 v[222:225], v37 offset:64
	ds_read_b128 v[226:229], v38 offset:64
	s_waitcnt lgkmcnt(11)
	v_mfma_f32_16x16x32_bf16 v[126:129], v[110:113], v[94:97], v[126:129]
	s_waitcnt vmcnt(11)
	ds_write_b128 v22, v[182:185]
	s_waitcnt vmcnt(7)
	ds_write_b128 v23, v[198:201]
	s_waitcnt lgkmcnt(12)
	v_mfma_f32_16x16x32_bf16 v[130:133], v[114:117], v[94:97], v[130:133]
	s_waitcnt lgkmcnt(11)
	v_mfma_f32_16x16x32_bf16 v[134:137], v[118:121], v[94:97], v[134:137]
	s_waitcnt lgkmcnt(10)
	v_mfma_f32_16x16x32_bf16 v[42:45], v[122:125], v[94:97], v[42:45]
	v_mfma_f32_16x16x32_bf16 v[58:61], v[110:113], v[98:101], v[58:61]
	ds_write_b128 v22, v[186:189] offset:10240
	s_waitcnt vmcnt(6)
	ds_write_b128 v25, v[202:205]
	v_mfma_f32_16x16x32_bf16 v[62:65], v[114:117], v[98:101], v[62:65]
	v_mfma_f32_16x16x32_bf16 v[74:77], v[118:121], v[98:101], v[74:77]
	v_mfma_f32_16x16x32_bf16 v[46:49], v[122:125], v[98:101], v[46:49]
	v_mfma_f32_16x16x32_bf16 v[66:69], v[110:113], v[102:105], v[66:69]
	ds_write_b128 v22, v[190:193] offset:20480
	v_mfma_f32_16x16x32_bf16 v[78:81], v[114:117], v[102:105], v[78:81]
	v_mfma_f32_16x16x32_bf16 v[82:85], v[118:121], v[102:105], v[82:85]
	v_mfma_f32_16x16x32_bf16 v[50:53], v[122:125], v[102:105], v[50:53]
	v_mfma_f32_16x16x32_bf16 v[70:73], v[110:113], v[106:109], v[70:73]
	ds_write_b128 v22, v[194:197] offset:30720
	v_mfma_f32_16x16x32_bf16 v[86:89], v[114:117], v[106:109], v[86:89]
	v_mfma_f32_16x16x32_bf16 v[90:93], v[118:121], v[106:109], v[90:93]
	v_mfma_f32_16x16x32_bf16 v[54:57], v[122:125], v[106:109], v[54:57]
	s_waitcnt lgkmcnt(0)
	s_barrier
	ds_read_b128 v[94:97], v39
	ds_read_b128 v[98:101], v39 offset:2560
	ds_read_b128 v[102:105], v39 offset:5120
	ds_read_b128 v[106:109], v39 offset:7680
	ds_read_b128 v[110:113], v40 offset:40960
	ds_read_b128 v[114:117], v40 offset:43520
	ds_read_b128 v[118:121], v40 offset:46080
	ds_read_b128 v[122:125], v40 offset:48640
	v_readlane_b32 s32, v251, 1
	s_add_i32 s32, s18, s32
	s_add_i32 s41, s0, 1
	s_cmpk_gt_i32 s32, 0x1cff
	s_cselect_b32 s32, s18, s32
	s_cselect_b32 s41, s0, s41
	v_readlane_b32 s42, v251, 12
	v_readlane_b32 s43, v251, 13
	s_and_b64 s[42:43], s[42:43], exec
	s_cbranch_scc0 .Lip_pf_lin
	s_lshl_b32 s42, s41, 5
	v_readlane_b32 s43, v251, 16
	s_add_i32 s42, s42, s43
	s_mul_hi_u32 s43, s42, 0x8d3dcb09
	s_lshr_b32 s43, s43, 7
	s_mul_i32 s98, s43, 0xe8
	s_sub_i32 s98, s42, s98
	s_lshl_b32 s43, s43, 2
	v_readlane_b32 s99, v251, 18
	s_lshr_b32 s42, s98, 2
	s_add_i32 s43, s43, s99
	s_and_b32 s98, s98, 3
	s_or_b32 s98, s43, s98
	s_branch .Lip_pf_go
